# P3: all pooling at phase start: pool blocks 3 items, sample blocks 1 item (+4 samples later)
# baseline (speedup 1.0000x reference)
; #define OPAQUE_TID() int tid = threadIdx.x; asm volatile("" : "+v"(tid)); const int lane = tid & 63, wave = __builtin_amdgcn_readfirstlane(tid >> 6); (void)lane; (void)wave
; __device__ __forceinline__ void pool_prepass(const Args& a) {
;     OPAQUE_TID();
;     const bf16_t* U = (const bf16_t*)(a.ws + WS_U);
;     bf16_t* PB = (bf16_t*)a.out;
;     const int G = gridDim.x, gq = wave & 3, ch = gq * 256 + (lane & 31) * 8;
;     for (int it = blockIdx.x; it < MT / 64; it += G) {
;         const int row0 = (it * 4 + (wave >> 2) * 2 + (lane >> 5)) * 16;
;         if (gq == 0) pool_run<2>(a, U, PB, row0, ch);
;         else if (gq == 1) pool_run<4>(a, U, PB, row0, ch);
;         else if (gq == 2) pool_run<8>(a, U, PB, row0, ch);
;         else pool_run<16>(a, U, PB, row0, ch);
;     }
; }
; __global__ void __launch_bounds__(512, 2) fwd_megakernel(Args a) {
;     ...
;         if ((bid >> 5) & 1) pool_prepass(a);
.LBB0_341:
	s_or_b64 exec, exec, s[0:1]
	s_bitcmp0_b32 s2, 5
	s_cselect_b64 s[40:41], -1, 0
	s_and_b64 vcc, exec, s[40:41]
	s_waitcnt lgkmcnt(0)
	s_barrier
	s_and_b32 s98, s2, 31
	s_lshr_b32 s99, s2, 6
	s_lshl_b32 s99, s99, 5
	s_or_b32 s98, s98, s99
	s_movk_i32 s99, 0x80
	s_movk_i32 s100, 0x180
	s_bitcmp1_b32 s2, 5
	s_cbranch_scc1 .Lpp_go
	s_addk_i32 s98, 0x180
	s_movk_i32 s100, 0x210
.Lpp_go:
	v_mov_b32_e32 v0, v180
	s_cmp_ge_i32 s98, s100
	v_readfirstlane_b32 s0, v0
	s_cbranch_scc1 .LBB0_642
	v_lshlrev_b32_e32 v1, 3, v0
	s_bfe_u32 s12, s0, 0x20006
	v_and_b32_e32 v1, 0xf8, v1
	s_ashr_i32 s0, s0, 7
	v_lshl_or_b32 v124, s12, 8, v1
	s_and_b32 s0, s0, -2
	s_lshl_b32 s1, s98, 2
	v_bfe_u32 v125, v0, 5, 1
	v_mov_b32_e32 v127, 0
	v_lshlrev_b32_e32 v126, 1, v124
	s_add_i32 s13, s1, s0
	v_lshl_add_u64 v[128:129], s[28:29], 0, v[126:127]
	v_lshl_add_u64 v[130:131], s[26:27], 0, v[126:127]
	v_lshlrev_b32_e32 v126, 2, v124
	v_or_b32_e32 v0, s13, v125
	v_lshl_add_u64 v[132:133], s[44:45], 0, v[126:127]
	s_lshl_b32 s14, s99, 2
	v_lshl_or_b32 v134, v0, 4, 15
	s_lshl_b32 s15, s99, 6
	s_movk_i32 s42, 0x7ff
	v_mov_b32_e32 v139, 0xfffff80f
	v_not_b32_e32 v170, 16
	v_mov_b32_e32 v171, 0x7ff
	s_movk_i32 s43, 0x3800
	s_mov_b32 s52, 0x3d800000
	s_mov_b32 s53, 0x3e000000
	s_mov_b32 s54, 0x3e800000
	v_mov_b32_e32 v172, 0x7f1
	v_mov_b32_e32 v173, 0x2100000
	v_mov_b32_e32 v174, 0x2540040
	v_mov_b32_e32 v175, 0x41800000
	v_mov_b32_e32 v176, 0x41000000
	s_mov_b32 s55, s98
	s_branch .LBB0_345
.LBB0_344:
	s_or_b64 exec, exec, s[0:1]
	s_add_i32 s55, s55, s99
	s_add_i32 s13, s13, s14
	s_cmp_lt_i32 s55, s100
	v_add_u32_e32 v134, s15, v134
	s_cbranch_scc0 .LBB0_642
